# speedup vs baseline: 1.0045x; 1.0045x over previous
; template <bool GDN, int NT> __device__ __forceinline__ void scan_load(const Frame& F, int b, int h, int dir, const ScanLane& L, int s, ScanOps<NT>& o) {
;     ...
;         const char* zq = upin((const char*)F.Z + ((size_t)chunk_row0(b, cidx) * ZW + ZC_LQ + h * 64) * 2);
; #pragma unroll
;         for (int ks = 0; ks < 2; ++ks) { o.Qf[ks] = ldu<bf16x8>(zq + ks * 64, L.zq); o.Mf[ks] = o.Qf[ks]; }
;         const char* base = (const char*)F.PM + (size_t)ud * 20480;
;         const char* bO = upin(base); const char* bB = upin(base + 10240);
; #pragma unroll
;         for (int pr = 0; pr < 2; ++pr) { const v4u qb = ldun<v4u>(bB + pr * 1024, L.o16p), qo = ldun<v4u>(bO + pr * 1024, L.o16p);
;             o.bv[2 * pr] = (v2u){qb.x, qb.y}; o.bv[2 * pr + 1] = (v2u){qb.z, qb.w}; o.ov[2 * pr] = (v2u){qo.x, qo.y}; o.ov[2 * pr + 1] = (v2u){qo.z, qo.w}; }
;         o.bv[4] = ldun<v2u>(bB + 2048, L.o8); o.ov[4] = ldun<v2u>(bO + 2048, L.o8);
;         o.wi = ldu<f32x4>(upin((const char*)F.WI + (size_t)ud * 256), L.wi);
;     ...
;     const float gl = ((const LAS float*)(St + 4 * 80 * 72))[(dir ? (s < 4 ? 3 - s : 39 - s) : s) * 2 + dir];
;     f32x4 O[NT];
; #pragma unroll
;     for (int t = 0; t < NT; ++t) {
;         const LAS bf16_t* sp2 = Sb + (16 * t + lr) * 72 + 8 * lq;
;         const bf16x8 s0 = *(const LAS bf16x8*)sp2, s1 = *(const LAS bf16x8*)(sp2 + 32);
;         const f32x4 bv = unpack4(use.bv[t]), ov = unpack4(use.ov[t]);
;         if (GDN) {
;             f32x4 o = ov, sn = S[t] * gl + bv;
;             o = __builtin_amdgcn_mfma_f32_16x16x32_bf16(use.Qf[0], s0, o, 0, 0, 0); o = __builtin_amdgcn_mfma_f32_16x16x32_bf16(use.Qf[1], s1, o, 0, 0, 0);
;             sn = __builtin_amdgcn_mfma_f32_16x16x32_bf16(use.Mf[0], s0, sn, 0, 0, 0); sn = __builtin_amdgcn_mfma_f32_16x16x32_bf16(use.Mf[1], s1, sn, 0, 0, 0);
;             S[t] = sn; O[t] = o;
;         } else {
;             f32x4 o = {0.f, 0.f, 0.f, 0.f};
;             o = __builtin_amdgcn_mfma_f32_16x16x32_bf16(use.Qf[0], s0, o, 0, 0, 0); o = __builtin_amdgcn_mfma_f32_16x16x32_bf16(use.Qf[1], s1, o, 0, 0, 0);
;             S[t] = S[t] * gl + bv; O[t] = o * use.wi + ov; }
;     }
;     if (!GDN) {
; #pragma unroll
;         for (int i = 0; i < 4; ++i) { const float den = row16_bcast<0>(O[NT - 1][i]), fl = row16_bcast<1>(O[NT - 1][i]); const float dv = frcp(fmaxf(fabsf(den), fl));
; #pragma unroll
.LBB0_346:
	s_add_i32 s0, s25, 5
	s_min_u32 s3, s0, 33
	s_add_i32 s6, s3, 2
	s_sub_i32 s3, 37, s3
	s_and_b64 s[4:5], s[90:91], exec
	s_cselect_b32 s3, s6, s3
	s_lshl_b32 s4, s3, 6
	s_add_i32 s4, s4, s33
	s_add_i32 s3, s3, s31
	s_mulk_i32 s4, 0xd00
	s_lshl_b32 s3, s3, 1
	s_or_b32 s4, s36, s4
	s_mov_b32 s5, s37
	s_add_i32 s92, s3, s68
	s_lshl_b64 s[4:5], s[4:5], 1
	s_add_u32 s4, s16, s4
	s_addc_u32 s5, s17, s5
	global_load_dwordx4 v[24:27], v28, s[4:5]
	global_load_dwordx4 v[20:23], v28, s[4:5] offset:64
	s_mul_i32 s4, s92, 0x5000
	v_readlane_b32 s5, v254, 46
	s_mul_hi_u32 s3, s92, 0x5000
	s_add_u32 s4, s5, s4
	v_readlane_b32 s5, v254, 47
	s_addc_u32 s5, s5, s3
	s_mov_b64 s[6:7], s[4:5]
	s_add_u32 s4, s4, 0x2800
	s_addc_u32 s5, s5, 0
	s_nop 0
	global_load_dwordx4 v[44:47], v32, s[4:5] nt
	global_load_dwordx4 v[28:31], v32, s[4:5] offset:1024 nt
	global_load_dwordx4 v[52:55], v32, s[6:7] nt
	s_nop 0
	global_load_dwordx4 v[32:35], v32, s[6:7] offset:1024 nt
	s_nop 0
	global_load_dwordx2 v[140:141], v100, s[4:5] offset:2048 nt
	global_load_dwordx2 v[138:139], v100, s[6:7] offset:2048 nt
	s_lshl_b64 s[4:5], s[92:93], 8
	v_readlane_b32 s6, v254, 52
	v_readlane_b32 s7, v254, 53
	s_add_u32 s4, s6, s4
	s_addc_u32 s5, s7, s5
	s_add_i32 s3, s24, 37
	v_lshl_add_u64 v[184:185], s[4:5], 0, v[0:1]
	s_and_b64 s[4:5], s[90:91], exec
	s_cselect_b32 s0, s0, s3
	s_lshl_b32 s0, s0, 3
	s_add_i32 s0, s34, s0
	v_mov_b32_e32 v0, s0
	ds_read_b32 v0, v0 offset:46080
	ds_read_b128 v[100:103], v203 offset:11520
	ds_read_b128 v[104:107], v203 offset:11584
	ds_read_b128 v[212:215], v203 offset:13824
	ds_read_b128 v[216:219], v203 offset:13888
	ds_read_b128 v[224:227], v203 offset:16128
	ds_read_b128 v[242:245], v203 offset:16192
	s_waitcnt lgkmcnt(5)
	v_mfma_f32_16x16x32_bf16 v[100:103], v[56:59], v[100:103], 0
	v_lshlrev_b32_e32 v108, 16, v84
	v_and_b32_e32 v109, 0xffff0000, v84
	v_lshlrev_b32_e32 v110, 16, v85
	s_waitcnt lgkmcnt(4)
	v_mfma_f32_16x16x32_bf16 v[100:103], v[48:51], v[104:107], v[100:103]
	v_and_b32_e32 v111, 0xffff0000, v85
	v_lshlrev_b32_e32 v112, 16, v88
	v_and_b32_e32 v113, 0xffff0000, v88
	v_lshlrev_b32_e32 v114, 16, v89
	v_and_b32_e32 v115, 0xffff0000, v89
	v_fma_f32 v150, v192, v0, v110
	v_fma_f32 v151, v193, v0, v111
	v_fma_f32 v148, v190, v0, v108
	v_fma_f32 v149, v191, v0, v109
	v_fma_f32 v108, v74, v102, v114
	v_fma_f32 v109, v75, v103, v115
	v_fma_f32 v110, v72, v100, v112
	v_fma_f32 v111, v73, v101, v113
	s_waitcnt lgkmcnt(3)
	v_mfma_f32_16x16x32_bf16 v[100:103], v[56:59], v[212:215], 0
	v_lshlrev_b32_e32 v112, 16, v86
	v_and_b32_e32 v113, 0xffff0000, v86
	v_lshlrev_b32_e32 v114, 16, v87
	s_waitcnt lgkmcnt(2)
	v_mfma_f32_16x16x32_bf16 v[100:103], v[48:51], v[216:219], v[100:103]
	ds_read_b128 v[212:215], v203 offset:18432
	ds_read_b128 v[216:219], v203 offset:18496
	v_and_b32_e32 v115, 0xffff0000, v87
	v_lshlrev_b32_e32 v116, 16, v90
	v_and_b32_e32 v117, 0xffff0000, v90
	v_lshlrev_b32_e32 v118, 16, v91
	v_and_b32_e32 v119, 0xffff0000, v91
	v_fma_f32 v152, v188, v0, v114
	v_fma_f32 v153, v189, v0, v115
	v_fma_f32 v154, v154, v0, v112
	v_fma_f32 v155, v155, v0, v113
	s_nop 0
	v_fma_f32 v112, v74, v102, v118
	v_fma_f32 v113, v75, v103, v119
	v_fma_f32 v114, v72, v100, v116
	v_fma_f32 v115, v73, v101, v117
	s_waitcnt lgkmcnt(3)
	v_mfma_f32_16x16x32_bf16 v[100:103], v[56:59], v[224:227], 0
	v_lshlrev_b32_e32 v116, 16, v76
	v_and_b32_e32 v117, 0xffff0000, v76
	v_lshlrev_b32_e32 v118, 16, v77
	s_waitcnt lgkmcnt(2)
	v_mfma_f32_16x16x32_bf16 v[100:103], v[48:51], v[242:245], v[100:103]
	ds_read_b128 v[224:227], v203 offset:20736
	ds_read_b128 v[242:245], v203 offset:20800
	v_and_b32_e32 v119, 0xffff0000, v77
	v_lshlrev_b32_e32 v160, 16, v80
	v_and_b32_e32 v161, 0xffff0000, v80
	v_lshlrev_b32_e32 v166, 16, v81
	v_and_b32_e32 v167, 0xffff0000, v81
	v_fma_f32 v156, v186, v0, v118
	v_fma_f32 v157, v187, v0, v119
	v_fma_f32 v158, v182, v0, v116
	v_fma_f32 v159, v183, v0, v117
	s_nop 0
	v_fma_f32 v116, v74, v102, v166
	v_fma_f32 v117, v75, v103, v167
	v_fma_f32 v118, v72, v100, v160
	v_fma_f32 v119, v73, v101, v161
	s_waitcnt lgkmcnt(3)
	v_mfma_f32_16x16x32_bf16 v[100:103], v[56:59], v[212:215], 0
	v_lshlrev_b32_e32 v166, 16, v78
	v_and_b32_e32 v167, 0xffff0000, v78
	v_lshlrev_b32_e32 v160, 16, v79
	s_waitcnt lgkmcnt(2)
	v_mfma_f32_16x16x32_bf16 v[100:103], v[48:51], v[216:219], v[100:103]
	v_and_b32_e32 v161, 0xffff0000, v79
	v_lshlrev_b32_e32 v168, 16, v82
	v_and_b32_e32 v169, 0xffff0000, v82
	v_lshlrev_b32_e32 v170, 16, v83
	v_and_b32_e32 v171, 0xffff0000, v83
	v_fma_f32 v160, v162, v0, v160
	v_fma_f32 v161, v163, v0, v161
	v_fma_f32 v162, v178, v0, v166
	v_fma_f32 v163, v179, v0, v167
	s_nop 0
	v_fma_f32 v166, v74, v102, v170
	v_fma_f32 v167, v75, v103, v171
	v_fma_f32 v168, v72, v100, v168
	v_fma_f32 v169, v73, v101, v169
	s_waitcnt lgkmcnt(1)
	v_mfma_f32_16x16x32_bf16 v[100:103], v[56:59], v[224:227], 0
	v_lshlrev_b32_e32 v174, 16, v2
	v_and_b32_e32 v175, 0xffff0000, v2
	v_lshlrev_b32_e32 v176, 16, v3
	s_waitcnt lgkmcnt(0)
	v_mfma_f32_16x16x32_bf16 v[100:103], v[48:51], v[242:245], v[100:103]
	v_and_b32_e32 v177, 0xffff0000, v3
	v_lshlrev_b32_e32 v170, 16, v144
	v_and_b32_e32 v171, 0xffff0000, v144
	v_lshlrev_b32_e32 v172, 16, v145
	v_and_b32_e32 v173, 0xffff0000, v145
	s_nop 2
	v_fma_f32 v100, v72, v100, v174
	v_fma_f32 v101, v73, v101, v175
	v_fma_f32 v102, v74, v102, v176
	v_fma_f32 v103, v75, v103, v177
	v_fma_f32 v178, v164, v0, v172
	v_fma_f32 v179, v165, v0, v173
	v_mov_b32_dpp v104, v100 row_newbcast:1 row_mask:0xf bank_mask:0xf bound_ctrl:1
	v_max_f32_dpp v100, |v100|, v104 row_newbcast:0 row_mask:0xf bank_mask:0xf bound_ctrl:1
	v_rcp_f32_e32 v100, v100
	v_mov_b32_dpp v104, v101 row_newbcast:1 row_mask:0xf bank_mask:0xf bound_ctrl:1
	v_max_f32_dpp v101, |v101|, v104 row_newbcast:0 row_mask:0xf bank_mask:0xf bound_ctrl:1
	v_rcp_f32_e32 v101, v101
	v_mov_b32_dpp v104, v102 row_newbcast:1 row_mask:0xf bank_mask:0xf bound_ctrl:1
	v_max_f32_dpp v102, |v102|, v104 row_newbcast:0 row_mask:0xf bank_mask:0xf bound_ctrl:1
	v_rcp_f32_e32 v102, v102
	v_mov_b32_dpp v104, v103 row_newbcast:1 row_mask:0xf bank_mask:0xf bound_ctrl:1
	v_max_f32_dpp v103, |v103|, v104 row_newbcast:0 row_mask:0xf bank_mask:0xf bound_ctrl:1
	v_rcp_f32_e32 v103, v103
	v_fma_f32 v164, v180, v0, v170
	v_fma_f32 v165, v181, v0, v171
	v_pk_mul_f32 v[104:105], v[110:111], v[100:101]
	s_add_i32 s3, s24, -6
	v_pk_mul_f32 v[106:107], v[108:109], v[102:103]
	v_pk_mul_f32 v[108:109], v[114:115], v[100:101]
	v_pk_mul_f32 v[110:111], v[112:113], v[102:103]
	v_pk_mul_f32 v[112:113], v[118:119], v[100:101]
	v_pk_mul_f32 v[114:115], v[116:117], v[102:103]
	v_pk_mul_f32 v[116:117], v[168:169], v[100:101]
	v_pk_mul_f32 v[118:119], v[166:167], v[102:103]
	s_mov_b64 s[20:21], 0
	v_mov_b32_e32 v183, v179
	v_mov_b32_e32 v182, v178
	v_mov_b32_e32 v181, v165
	v_mov_b32_e32 v180, v164

; template <bool GDN, int NT> __device__ __forceinline__ void scan_load(const Frame& F, int b, int h, int dir, const ScanLane& L, int s, ScanOps<NT>& o) {
;     ...
;         const char* zq = upin((const char*)F.Z + ((size_t)chunk_row0(b, cidx) * ZW + ZC_LQ + h * 64) * 2);
; #pragma unroll
;         for (int ks = 0; ks < 2; ++ks) { o.Qf[ks] = ldu<bf16x8>(zq + ks * 64, L.zq); o.Mf[ks] = o.Qf[ks]; }
;         const char* base = (const char*)F.PM + (size_t)ud * 20480;
;         const char* bO = upin(base); const char* bB = upin(base + 10240);
; #pragma unroll
;         for (int pr = 0; pr < 2; ++pr) { const v4u qb = ldun<v4u>(bB + pr * 1024, L.o16p), qo = ldun<v4u>(bO + pr * 1024, L.o16p);
;             o.bv[2 * pr] = (v2u){qb.x, qb.y}; o.bv[2 * pr + 1] = (v2u){qb.z, qb.w}; o.ov[2 * pr] = (v2u){qo.x, qo.y}; o.ov[2 * pr + 1] = (v2u){qo.z, qo.w}; }
;         o.bv[4] = ldun<v2u>(bB + 2048, L.o8); o.ov[4] = ldun<v2u>(bO + 2048, L.o8);
;         o.wi = ldu<f32x4>(upin((const char*)F.WI + (size_t)ud * 256), L.wi);
;     ...
;     const float gl = ((const LAS float*)(St + 4 * 80 * 72))[(dir ? (s < 4 ? 3 - s : 39 - s) : s) * 2 + dir];
;     f32x4 O[NT];
; #pragma unroll
;     for (int t = 0; t < NT; ++t) {
;         const LAS bf16_t* sp2 = Sb + (16 * t + lr) * 72 + 8 * lq;
;         const bf16x8 s0 = *(const LAS bf16x8*)sp2, s1 = *(const LAS bf16x8*)(sp2 + 32);
;         const f32x4 bv = unpack4(use.bv[t]), ov = unpack4(use.ov[t]);
;         if (GDN) {
;             f32x4 o = ov, sn = S[t] * gl + bv;
;             o = __builtin_amdgcn_mfma_f32_16x16x32_bf16(use.Qf[0], s0, o, 0, 0, 0); o = __builtin_amdgcn_mfma_f32_16x16x32_bf16(use.Qf[1], s1, o, 0, 0, 0);
;             sn = __builtin_amdgcn_mfma_f32_16x16x32_bf16(use.Mf[0], s0, sn, 0, 0, 0); sn = __builtin_amdgcn_mfma_f32_16x16x32_bf16(use.Mf[1], s1, sn, 0, 0, 0);
;             S[t] = sn; O[t] = o;
;         } else {
;             f32x4 o = {0.f, 0.f, 0.f, 0.f};
;             o = __builtin_amdgcn_mfma_f32_16x16x32_bf16(use.Qf[0], s0, o, 0, 0, 0); o = __builtin_amdgcn_mfma_f32_16x16x32_bf16(use.Qf[1], s1, o, 0, 0, 0);
;             S[t] = S[t] * gl + bv; O[t] = o * use.wi + ov; }
;     }
;     if (!GDN) {
; #pragma unroll
;         for (int i = 0; i < 4; ++i) { const float den = row16_bcast<0>(O[NT - 1][i]), fl = row16_bcast<1>(O[NT - 1][i]); const float dv = frcp(fmaxf(fabsf(den), fl));
; #pragma unroll
.LBB0_361:
	s_min_u32 s1, s25, 33
	s_add_i32 s1, s1, 2
	s_and_b64 s[4:5], exec, s[10:11]
	s_cselect_b32 s3, 3, 39
	s_sub_i32 s3, s3, s1
	s_and_b64 s[4:5], s[90:91], exec
	s_cselect_b32 s1, s1, s3
	s_lshl_b32 s3, s1, 6
	s_cmp_lt_i32 s1, 4
	s_cselect_b32 s4, s63, s33
	s_add_i32 s3, s4, s3
	s_mul_i32 s6, s3, 0xd00
	s_add_i32 s1, s1, s31
	s_ashr_i32 s7, s6, 31
	s_lshl_b32 s1, s1, 1
	s_or_b64 s[6:7], s[36:37], s[6:7]
	s_add_i32 s4, s1, s68
	s_lshl_b64 s[6:7], s[6:7], 1
	s_add_u32 s6, s16, s6
	s_addc_u32 s7, s17, s7
	global_load_dwordx4 v[56:59], v186, s[6:7]
	global_load_dwordx4 v[48:51], v186, s[6:7] offset:64
	s_ashr_i32 s5, s4, 31
	s_mul_i32 s3, s4, 0x5000
	v_readlane_b32 s6, v254, 46
	s_mul_hi_i32 s1, s4, 0x5000
	s_add_u32 s6, s6, s3
	v_readlane_b32 s3, v254, 47
	s_addc_u32 s7, s3, s1
	s_mov_b64 s[8:9], s[6:7]
	s_add_u32 s6, s6, 0x2800
	s_addc_u32 s7, s7, 0
	global_load_dwordx4 v[84:87], v185, s[6:7] nt
	global_load_dwordx4 v[88:91], v185, s[8:9] nt
	global_load_dwordx4 v[76:79], v185, s[6:7] offset:1024 nt
	global_load_dwordx4 v[80:83], v185, s[8:9] offset:1024 nt
	global_load_dwordx2 v[144:145], v184, s[6:7] offset:2048 nt
	global_load_dwordx2 v[2:3], v184, s[8:9] offset:2048 nt
	s_lshl_b64 s[4:5], s[4:5], 8
	v_readlane_b32 s6, v254, 52
	v_readlane_b32 s7, v254, 53
	s_add_u32 s4, s6, s4
	s_addc_u32 s5, s7, s5
	s_cmp_gt_u32 s25, 3
	s_cselect_b32 s1, 39, 3
	s_add_i32 s1, s1, s24
	s_add_i32 s1, s1, 3
	global_load_dwordx4 v[72:75], v0, s[4:5]
	s_and_b64 s[4:5], s[90:91], exec
	s_cselect_b32 s1, s25, s1
	s_lshl_b32 s1, s1, 3
	s_add_i32 s1, s34, s1
	v_mov_b32_e32 v0, s1
	v_add_u32_e32 v164, v201, v121
	ds_read_b32 v0, v0 offset:46080
	ds_read_b128 v[104:107], v164
	ds_read_b128 v[108:111], v164 offset:64
	ds_read_b128 v[212:215], v164 offset:2304
	ds_read_b128 v[216:219], v164 offset:2368
	ds_read_b128 v[224:227], v164 offset:4608
	ds_read_b128 v[242:245], v164 offset:4672
	s_waitcnt lgkmcnt(5)
	v_mfma_f32_16x16x32_bf16 v[104:107], v[40:43], v[104:107], 0
	v_lshlrev_b32_e32 v112, 16, v92
	v_and_b32_e32 v113, 0xffff0000, v92
	v_lshlrev_b32_e32 v92, 16, v93
	s_waitcnt lgkmcnt(4)
	v_mfma_f32_16x16x32_bf16 v[104:107], v[36:39], v[108:111], v[104:107]
	v_and_b32_e32 v93, 0xffff0000, v93
	v_lshlrev_b32_e32 v114, 16, v96
	v_and_b32_e32 v115, 0xffff0000, v96
	v_lshlrev_b32_e32 v96, 16, v97
	v_and_b32_e32 v97, 0xffff0000, v97
	v_fma_f32 v150, v150, v0, v92
	v_fma_f32 v151, v151, v0, v93
	s_nop 1
	v_fma_f32 v92, v62, v106, v96
	v_fma_f32 v93, v63, v107, v97
	v_fma_f32 v96, v60, v104, v114
	v_fma_f32 v97, v61, v105, v115
	s_waitcnt lgkmcnt(3)
	v_mfma_f32_16x16x32_bf16 v[104:107], v[40:43], v[212:215], 0
	v_fma_f32 v148, v148, v0, v112
	v_fma_f32 v149, v149, v0, v113
	v_lshlrev_b32_e32 v112, 16, v94
	v_and_b32_e32 v113, 0xffff0000, v94
	s_waitcnt lgkmcnt(2)
	v_mfma_f32_16x16x32_bf16 v[104:107], v[36:39], v[216:219], v[104:107]
	ds_read_b128 v[212:215], v164 offset:6912
	ds_read_b128 v[216:219], v164 offset:6976
	v_lshlrev_b32_e32 v94, 16, v95
	v_and_b32_e32 v95, 0xffff0000, v95
	v_lshlrev_b32_e32 v114, 16, v98
	v_and_b32_e32 v115, 0xffff0000, v98
	v_lshlrev_b32_e32 v98, 16, v99
	v_and_b32_e32 v99, 0xffff0000, v99
	v_fma_f32 v152, v152, v0, v94
	v_fma_f32 v153, v153, v0, v95
	s_nop 0
	v_fma_f32 v94, v62, v106, v98
	v_fma_f32 v95, v63, v107, v99
	v_fma_f32 v98, v60, v104, v114
	v_fma_f32 v99, v61, v105, v115
	s_waitcnt lgkmcnt(3)
	v_mfma_f32_16x16x32_bf16 v[104:107], v[40:43], v[224:227], 0
	v_fma_f32 v154, v154, v0, v112
	v_fma_f32 v155, v155, v0, v113
	v_lshlrev_b32_e32 v112, 16, v64
	v_and_b32_e32 v113, 0xffff0000, v64
	s_waitcnt lgkmcnt(2)
	v_mfma_f32_16x16x32_bf16 v[104:107], v[36:39], v[242:245], v[104:107]
	ds_read_b128 v[224:227], v164 offset:9216
	ds_read_b128 v[242:245], v164 offset:9280
	v_lshlrev_b32_e32 v114, 16, v68
	v_and_b32_e32 v115, 0xffff0000, v68
	v_lshlrev_b32_e32 v68, 16, v69
	v_and_b32_e32 v69, 0xffff0000, v69
	v_fma_f32 v158, v158, v0, v112
	v_fma_f32 v159, v159, v0, v113
	s_nop 2
	v_fma_f32 v116, v62, v106, v68
	v_fma_f32 v117, v63, v107, v69
	v_fma_f32 v112, v60, v104, v114
	v_fma_f32 v113, v61, v105, v115
	v_lshlrev_b32_e32 v64, 16, v65
	v_and_b32_e32 v65, 0xffff0000, v65
	v_fma_f32 v156, v156, v0, v64
	v_fma_f32 v157, v157, v0, v65
	v_lshlrev_b32_e32 v68, 16, v66
	v_and_b32_e32 v69, 0xffff0000, v66
	v_lshlrev_b32_e32 v114, 16, v67
	v_and_b32_e32 v115, 0xffff0000, v67
	s_waitcnt lgkmcnt(3)
	v_mfma_f32_16x16x32_bf16 v[64:67], v[40:43], v[212:215], 0
	v_lshlrev_b32_e32 v118, 16, v70
	v_and_b32_e32 v119, 0xffff0000, v70
	v_lshlrev_b32_e32 v70, 16, v71
	s_waitcnt lgkmcnt(2)
	v_mfma_f32_16x16x32_bf16 v[64:67], v[36:39], v[216:219], v[64:67]
	v_and_b32_e32 v71, 0xffff0000, v71
	v_fma_f32 v162, v162, v0, v68
	v_fma_f32 v163, v163, v0, v69
	v_lshlrev_b32_e32 v108, 16, v142
	v_and_b32_e32 v109, 0xffff0000, v142
	v_lshlrev_b32_e32 v104, 16, v146
	s_nop 2
	v_fma_f32 v166, v62, v66, v70
	v_fma_f32 v167, v63, v67, v71
	v_fma_f32 v118, v60, v64, v118
	v_fma_f32 v119, v61, v65, v119
	s_waitcnt lgkmcnt(1)
	v_mfma_f32_16x16x32_bf16 v[40:43], v[40:43], v[224:227], 0
	v_and_b32_e32 v105, 0xffff0000, v146
	v_lshlrev_b32_e32 v106, 16, v147
	v_and_b32_e32 v107, 0xffff0000, v147
	s_waitcnt lgkmcnt(0)
	v_mfma_f32_16x16x32_bf16 v[36:39], v[36:39], v[242:245], v[40:43]
	v_fma_f32 v160, v160, v0, v114
	v_fma_f32 v161, v161, v0, v115
	v_fma_f32 v178, v182, v0, v106
	v_fma_f32 v179, v183, v0, v107
	v_fma_f32 v164, v180, v0, v104
	v_fma_f32 v165, v181, v0, v105
	v_lshlrev_b32_e32 v110, 16, v143
	v_and_b32_e32 v111, 0xffff0000, v143
	s_nop 1
	v_fma_f32 v36, v60, v36, v108
	v_fma_f32 v37, v61, v37, v109
	v_fma_f32 v38, v62, v38, v110
	v_fma_f32 v39, v63, v39, v111
	s_nop 0
	v_mov_b32_dpp v0, v36 row_newbcast:1 row_mask:0xf bank_mask:0xf bound_ctrl:1
	v_max_f32_dpp v0, |v36|, v0 row_newbcast:0 row_mask:0xf bank_mask:0xf bound_ctrl:1
	v_rcp_f32_e32 v36, v0
	s_nop 0
	v_mov_b32_dpp v0, v37 row_newbcast:1 row_mask:0xf bank_mask:0xf bound_ctrl:1
	v_max_f32_dpp v0, |v37|, v0 row_newbcast:0 row_mask:0xf bank_mask:0xf bound_ctrl:1
	v_rcp_f32_e32 v37, v0
	s_nop 0
	v_mov_b32_dpp v0, v38 row_newbcast:1 row_mask:0xf bank_mask:0xf bound_ctrl:1
	v_max_f32_dpp v0, |v38|, v0 row_newbcast:0 row_mask:0xf bank_mask:0xf bound_ctrl:1
	v_rcp_f32_e32 v38, v0
	v_pk_mul_f32 v[104:105], v[96:97], v[36:37]
	v_mov_b32_dpp v0, v39 row_newbcast:1 row_mask:0xf bank_mask:0xf bound_ctrl:1
	v_max_f32_dpp v0, |v39|, v0 row_newbcast:0 row_mask:0xf bank_mask:0xf bound_ctrl:1
	v_rcp_f32_e32 v39, v0
	v_pk_mul_f32 v[108:109], v[98:99], v[36:37]
	v_pk_mul_f32 v[112:113], v[112:113], v[36:37]
	v_pk_mul_f32 v[106:107], v[92:93], v[38:39]
	v_pk_mul_f32 v[110:111], v[94:95], v[38:39]
	v_pk_mul_f32 v[114:115], v[116:117], v[38:39]
	v_pk_mul_f32 v[116:117], v[118:119], v[36:37]
	v_pk_mul_f32 v[118:119], v[166:167], v[38:39]

; template <bool GDN, int NT> __device__ __forceinline__ void scan_load(const Frame& F, int b, int h, int dir, const ScanLane& L, int s, ScanOps<NT>& o) {
;     ...
;         const char* zq = upin((const char*)F.Z + ((size_t)chunk_row0(b, cidx) * ZW + ZC_LQ + h * 64) * 2);
; #pragma unroll
;         for (int ks = 0; ks < 2; ++ks) { o.Qf[ks] = ldu<bf16x8>(zq + ks * 64, L.zq); o.Mf[ks] = o.Qf[ks]; }
;         const char* base = (const char*)F.PM + (size_t)ud * 20480;
;         const char* bO = upin(base); const char* bB = upin(base + 10240);
; #pragma unroll
;         for (int pr = 0; pr < 2; ++pr) { const v4u qb = ldun<v4u>(bB + pr * 1024, L.o16p), qo = ldun<v4u>(bO + pr * 1024, L.o16p);
;             o.bv[2 * pr] = (v2u){qb.x, qb.y}; o.bv[2 * pr + 1] = (v2u){qb.z, qb.w}; o.ov[2 * pr] = (v2u){qo.x, qo.y}; o.ov[2 * pr + 1] = (v2u){qo.z, qo.w}; }
;         o.bv[4] = ldun<v2u>(bB + 2048, L.o8); o.ov[4] = ldun<v2u>(bO + 2048, L.o8);
;         o.wi = ldu<f32x4>(upin((const char*)F.WI + (size_t)ud * 256), L.wi);
;     ...
;     LAS bf16_t* Sb = St + ((dir * 2 + (s & 1)) * 80) * 72;
;     if (s < 36) {
; #pragma unroll
;         for (int t = 0; t < NT; ++t) *(LAS v2u*)(Sb + (16 * t + lr) * 72 + 16 * wq + 4 * lq) = pack4(S[t]); }
;     if (s == 21 || s == 3) asm volatile("s_waitcnt vmcnt(0)" ::: "memory");
;     else if (scan_needfin(s - 1)) { if (GDN) asm volatile("s_waitcnt vmcnt(14)" ::: "memory"); else asm volatile("s_waitcnt vmcnt(15)" ::: "memory"); }
;     else { if (GDN) asm volatile("s_waitcnt vmcnt(8)" ::: "memory"); else asm volatile("s_waitcnt vmcnt(9)" ::: "memory"); }
;     __syncthreads();
;     if (s > 0) {
;         const int sp = s - 1;
;         if (sp == 20 || sp == 2) { asm volatile("s_waitcnt vmcnt(0)" ::: "memory"); scan_fin_load<GDN>(F, b, h, dir, L, sp, PEND, fin); }
;         if (!nofin) scan_finish<GDN>(F, b, h, dir, L, sp, PEND, Oprev, fin);
;     }
;     if (s == 36) return false;
;     if (scan_needfin(s) && ko != 1 && ko != 3) scan_fin_load<GDN>(F, b, h, dir, L, s + 1, PEND, fin);
;     if (ko != 1 && ko != 2) scan_load<GDN, NT>(F, b, h, dir, L, s < 34 ? s + 2 : 35, ld);
;     const float gl = ((const LAS float*)(St + 4 * 80 * 72))[(dir ? (s < 4 ? 3 - s : 39 - s) : s) * 2 + dir];
;     f32x4 O[NT];
; #pragma unroll
;     for (int t = 0; t < NT; ++t) {
;         const LAS bf16_t* sp2 = Sb + (16 * t + lr) * 72 + 8 * lq;
.LBB0_396:
	s_min_u32 s1, s4, 33
	s_add_i32 s8, s1, 2
	s_and_b64 s[6:7], exec, s[10:11]
	s_cselect_b32 s1, 3, 39
	s_sub_i32 s9, s1, s8
	s_and_b64 s[6:7], s[90:91], exec
	s_cselect_b32 s6, s8, s9
	s_lshl_b32 s7, s6, 6
	s_cmp_lt_i32 s6, 4
	s_cselect_b32 s8, s63, s33
	s_add_i32 s7, s8, s7
	s_mul_i32 s8, s7, 0xd00
	s_add_i32 s6, s6, s31
	s_ashr_i32 s9, s8, 31
	s_lshl_b32 s6, s6, 1
	s_or_b64 s[8:9], s[36:37], s[8:9]
	s_add_i32 s6, s6, s68
	s_lshl_b64 s[8:9], s[8:9], 1
	s_add_u32 s8, s16, s8
	s_addc_u32 s9, s17, s9
	global_load_dwordx4 v[40:43], v36, s[8:9]
	s_nop 0
	global_load_dwordx4 v[36:39], v36, s[8:9] offset:64
	s_ashr_i32 s7, s6, 31
	s_mul_i32 s8, s6, 0x5000
	v_readlane_b32 s10, v254, 46
	s_mul_hi_i32 s9, s6, 0x5000
	s_add_u32 s8, s10, s8
	v_readlane_b32 s10, v254, 47
	s_addc_u32 s9, s10, s9
	s_mov_b64 s[10:11], s[8:9]
	s_add_u32 s8, s8, 0x2800
	s_addc_u32 s9, s9, 0
	global_load_dwordx4 v[92:95], v60, s[8:9] nt
	global_load_dwordx4 v[64:67], v60, s[8:9] offset:1024 nt
	global_load_dwordx4 v[96:99], v60, s[10:11] nt
	global_load_dwordx4 v[68:71], v60, s[10:11] offset:1024 nt
	global_load_dwordx2 v[146:147], v61, s[8:9] offset:2048 nt
	global_load_dwordx2 v[142:143], v61, s[10:11] offset:2048 nt
	s_lshl_b64 s[6:7], s[6:7], 8
	v_readlane_b32 s8, v254, 52
	v_readlane_b32 s9, v254, 53
	s_add_u32 s6, s8, s6
	s_addc_u32 s7, s9, s7
	global_load_dwordx4 v[60:63], v0, s[6:7]
	s_add_i32 s5, s5, 2
	s_and_b64 s[6:7], s[90:91], exec
	s_cselect_b32 s5, s4, s5
	s_lshl_b32 s6, s5, 3
	s_add_i32 s6, s34, s6
	v_mov_b32_e32 v0, s6
	v_add_u32_e32 v203, v201, v121
	ds_read_b128 v[104:107], v203 offset:11520
	ds_read_b32 v0, v0 offset:46080
	ds_read_b128 v[108:111], v203 offset:11584
	ds_read_b128 v[212:215], v203 offset:13824
	ds_read_b128 v[216:219], v203 offset:13888
	ds_read_b128 v[224:227], v203 offset:16128
	ds_read_b128 v[242:245], v203 offset:18432
	s_waitcnt lgkmcnt(6)
	v_mfma_f32_16x16x32_bf16 v[104:107], v[24:27], v[104:107], 0
	v_lshlrev_b32_e32 v116, 16, v44
	v_and_b32_e32 v117, 0xffff0000, v44
	v_lshlrev_b32_e32 v118, 16, v45
	v_and_b32_e32 v119, 0xffff0000, v45
	s_waitcnt lgkmcnt(4)
	v_mfma_f32_16x16x32_bf16 v[104:107], v[20:23], v[108:111], v[104:107]
	v_fma_f32 v180, v150, v0, v118
	v_fma_f32 v181, v151, v0, v119
	v_fma_f32 v182, v148, v0, v116
	v_fma_f32 v183, v149, v0, v117
	s_waitcnt lgkmcnt(3)
	v_mfma_f32_16x16x32_bf16 v[112:115], v[24:27], v[212:215], 0
	v_lshlrev_b32_e32 v148, 16, v46
	s_waitcnt lgkmcnt(2)
	v_mfma_f32_16x16x32_bf16 v[108:111], v[20:23], v[216:219], v[112:115]
	ds_read_b128 v[212:215], v203 offset:16192
	ds_read_b128 v[216:219], v203 offset:18496
	v_and_b32_e32 v149, 0xffff0000, v46
	v_lshlrev_b32_e32 v150, 16, v47
	v_and_b32_e32 v151, 0xffff0000, v47
	s_waitcnt lgkmcnt(3)
	v_mfma_f32_16x16x32_bf16 v[116:119], v[24:27], v[224:227], 0
	v_fma_f32 v150, v152, v0, v150
	v_fma_f32 v151, v153, v0, v151
	v_fma_f32 v154, v154, v0, v148
	v_fma_f32 v155, v155, v0, v149
	v_lshlrev_b32_e32 v152, 16, v28
	v_and_b32_e32 v153, 0xffff0000, v28
	v_lshlrev_b32_e32 v148, 16, v29
	v_and_b32_e32 v149, 0xffff0000, v29
	s_waitcnt lgkmcnt(1)
	v_mfma_f32_16x16x32_bf16 v[112:115], v[20:23], v[212:215], v[116:119]
	v_fma_f32 v148, v156, v0, v148
	v_fma_f32 v149, v157, v0, v149
	v_fma_f32 v152, v158, v0, v152
	v_fma_f32 v153, v159, v0, v153
	v_lshlrev_b32_e32 v170, 16, v30
	v_mfma_f32_16x16x32_bf16 v[156:159], v[24:27], v[242:245], 0
	ds_read_b128 v[224:227], v203 offset:20736
	ds_read_b128 v[242:245], v203 offset:20800
	v_and_b32_e32 v171, 0xffff0000, v30
	v_lshlrev_b32_e32 v172, 16, v31
	s_waitcnt lgkmcnt(2)
	v_mfma_f32_16x16x32_bf16 v[116:119], v[20:23], v[216:219], v[156:159]
	v_and_b32_e32 v173, 0xffff0000, v31
	v_fma_f32 v184, v160, v0, v172
	v_fma_f32 v185, v161, v0, v173
	v_fma_f32 v160, v162, v0, v170
	v_fma_f32 v161, v163, v0, v171
	s_waitcnt lgkmcnt(1)
	v_mfma_f32_16x16x32_bf16 v[166:169], v[24:27], v[224:227], 0
	v_lshlrev_b32_e32 v162, 16, v140
	v_and_b32_e32 v163, 0xffff0000, v140
	v_lshlrev_b32_e32 v172, 16, v138
	s_waitcnt lgkmcnt(0)
	v_mfma_f32_16x16x32_bf16 v[166:169], v[20:23], v[242:245], v[166:169]
	v_and_b32_e32 v173, 0xffff0000, v138
	v_lshlrev_b32_e32 v174, 16, v139
	v_and_b32_e32 v175, 0xffff0000, v139
	v_lshlrev_b32_e32 v170, 16, v141
	v_and_b32_e32 v171, 0xffff0000, v141
	v_fma_f32 v158, v164, v0, v162
	v_fma_f32 v159, v165, v0, v163
	s_nop 0
	v_fma_f32 v168, v102, v168, v174
	v_fma_f32 v169, v103, v169, v175
	v_fma_f32 v162, v100, v166, v172
	v_fma_f32 v163, v101, v167, v173
	v_fma_f32 v156, v178, v0, v170
	v_fma_f32 v157, v179, v0, v171
	v_mov_b32_dpp v165, v168 row_newbcast:0 row_mask:0xf bank_mask:0xf bound_ctrl:1
	v_mov_b32_dpp v187, v162 row_newbcast:0 row_mask:0xf bank_mask:0xf bound_ctrl:1
	v_mov_b32_dpp v193, v162 row_newbcast:1 row_mask:0xf bank_mask:0xf bound_ctrl:1
	v_mov_b32_dpp v179, v163 row_newbcast:0 row_mask:0xf bank_mask:0xf bound_ctrl:1
	v_mov_b32_dpp v186, v163 row_newbcast:1 row_mask:0xf bank_mask:0xf bound_ctrl:1
	v_mov_b32_dpp v178, v168 row_newbcast:1 row_mask:0xf bank_mask:0xf bound_ctrl:1
	v_mov_b32_dpp v163, v169 row_newbcast:0 row_mask:0xf bank_mask:0xf bound_ctrl:1
	v_mov_b32_dpp v164, v169 row_newbcast:1 row_mask:0xf bank_mask:0xf bound_ctrl:1
	v_mov_b32_e32 v0, v120
	v_mov_b32_e32 v191, v197
	v_mov_b32_e32 v188, v194
	v_mov_b32_e32 v190, v196
	v_mov_b32_e32 v192, v199
	v_mov_b32_e32 v166, v198
	v_mov_b32_e32 v162, v200
	v_mov_b32_e32 v189, v195
	s_cmp_gt_u32 s25, 33
	s_cbranch_scc1 .LBB0_398
	v_cvt_pk_bf16_f32 v166, v182, v183
	v_cvt_pk_bf16_f32 v167, v180, v181
	ds_write_b64 v202, v[166:167]
	v_cvt_pk_bf16_f32 v166, v154, v155
	v_cvt_pk_bf16_f32 v167, v150, v151
	ds_write_b64 v202, v[166:167] offset:2304
	v_cvt_pk_bf16_f32 v166, v152, v153
	v_cvt_pk_bf16_f32 v167, v148, v149
	ds_write_b64 v202, v[166:167] offset:4608
	v_cvt_pk_bf16_f32 v166, v160, v161
	v_cvt_pk_bf16_f32 v167, v184, v185
	ds_write_b64 v202, v[166:167] offset:6912
	v_cvt_pk_bf16_f32 v166, v158, v159
	v_cvt_pk_bf16_f32 v167, v156, v157
	ds_write_b64 v202, v[166:167] offset:9216

; template <bool GDN, int NT> __device__ __forceinline__ void scan_load(const Frame& F, int b, int h, int dir, const ScanLane& L, int s, ScanOps<NT>& o) {
;     ...
;         const char* zq = upin((const char*)F.Z + ((size_t)chunk_row0(b, cidx) * ZW + ZC_LQ + h * 64) * 2);
; #pragma unroll
;         for (int ks = 0; ks < 2; ++ks) { o.Qf[ks] = ldu<bf16x8>(zq + ks * 64, L.zq); o.Mf[ks] = o.Qf[ks]; }
;         const char* base = (const char*)F.PM + (size_t)ud * 20480;
;         const char* bO = upin(base); const char* bB = upin(base + 10240);
; #pragma unroll
;         for (int pr = 0; pr < 2; ++pr) { const v4u qb = ldun<v4u>(bB + pr * 1024, L.o16p), qo = ldun<v4u>(bO + pr * 1024, L.o16p);
;             o.bv[2 * pr] = (v2u){qb.x, qb.y}; o.bv[2 * pr + 1] = (v2u){qb.z, qb.w}; o.ov[2 * pr] = (v2u){qo.x, qo.y}; o.ov[2 * pr + 1] = (v2u){qo.z, qo.w}; }
;         o.bv[4] = ldun<v2u>(bB + 2048, L.o8); o.ov[4] = ldun<v2u>(bO + 2048, L.o8);
;         o.wi = ldu<f32x4>(upin((const char*)F.WI + (size_t)ud * 256), L.wi);
;     ...
;     const float gl = ((const LAS float*)(St + 4 * 80 * 72))[(dir ? (s < 4 ? 3 - s : 39 - s) : s) * 2 + dir];
;     f32x4 O[NT];
; #pragma unroll
;     for (int t = 0; t < NT; ++t) {
;         const LAS bf16_t* sp2 = Sb + (16 * t + lr) * 72 + 8 * lq;
;         const bf16x8 s0 = *(const LAS bf16x8*)sp2, s1 = *(const LAS bf16x8*)(sp2 + 32);
;         const f32x4 bv = unpack4(use.bv[t]), ov = unpack4(use.ov[t]);
;         if (GDN) {
;             f32x4 o = ov, sn = S[t] * gl + bv;
;             o = __builtin_amdgcn_mfma_f32_16x16x32_bf16(use.Qf[0], s0, o, 0, 0, 0); o = __builtin_amdgcn_mfma_f32_16x16x32_bf16(use.Qf[1], s1, o, 0, 0, 0);
;             sn = __builtin_amdgcn_mfma_f32_16x16x32_bf16(use.Mf[0], s0, sn, 0, 0, 0); sn = __builtin_amdgcn_mfma_f32_16x16x32_bf16(use.Mf[1], s1, sn, 0, 0, 0);
;             S[t] = sn; O[t] = o;
;         } else {
;             f32x4 o = {0.f, 0.f, 0.f, 0.f};
;             o = __builtin_amdgcn_mfma_f32_16x16x32_bf16(use.Qf[0], s0, o, 0, 0, 0); o = __builtin_amdgcn_mfma_f32_16x16x32_bf16(use.Qf[1], s1, o, 0, 0, 0);
;             S[t] = S[t] * gl + bv; O[t] = o * use.wi + ov; }
;     }
;     if (!GDN) {
; #pragma unroll
;         for (int i = 0; i < 4; ++i) { const float den = row16_bcast<0>(O[NT - 1][i]), fl = row16_bcast<1>(O[NT - 1][i]); const float dv = frcp(fmaxf(fabsf(den), fl));
; #pragma unroll
.LBB0_409:
	s_min_u32 s5, s3, 33
	s_add_i32 s8, s5, 2
	s_sub_i32 s5, 37, s5
	s_and_b64 s[6:7], s[90:91], exec
	s_cselect_b32 s5, s8, s5
	s_lshl_b32 s6, s5, 6
	s_add_i32 s6, s6, s33
	s_add_i32 s5, s5, s31
	s_mulk_i32 s6, 0xd00
	s_lshl_b32 s5, s5, 1
	s_or_b32 s6, s36, s6
	s_mov_b32 s7, s37
	s_add_i32 s92, s5, s68
	s_lshl_b64 s[6:7], s[6:7], 1
	s_add_u32 s6, s16, s6
	s_addc_u32 s7, s17, s7
	global_load_dwordx4 v[24:27], v190, s[6:7]
	global_load_dwordx4 v[20:23], v190, s[6:7] offset:64
	s_mul_i32 s6, s92, 0x5000
	v_readlane_b32 s7, v254, 46
	s_mul_hi_u32 s5, s92, 0x5000
	s_add_u32 s6, s7, s6
	v_readlane_b32 s7, v254, 47
	s_addc_u32 s7, s7, s5
	s_mov_b64 s[8:9], s[6:7]
	s_add_u32 s6, s6, 0x2800
	s_addc_u32 s7, s7, 0
	s_nop 0
	global_load_dwordx4 v[44:47], v189, s[6:7] nt
	global_load_dwordx4 v[28:31], v189, s[6:7] offset:1024 nt
	global_load_dwordx4 v[52:55], v189, s[8:9] nt
	global_load_dwordx4 v[32:35], v189, s[8:9] offset:1024 nt
	global_load_dwordx2 v[140:141], v188, s[6:7] offset:2048 nt
	global_load_dwordx2 v[138:139], v188, s[8:9] offset:2048 nt
	s_lshl_b64 s[6:7], s[92:93], 8
	v_readlane_b32 s8, v254, 52
	v_readlane_b32 s9, v254, 53
	s_add_u32 s6, s8, s6
	s_addc_u32 s7, s9, s7
	global_load_dwordx4 v[100:103], v0, s[6:7]
	s_add_i32 s6, s4, 1
	s_and_b64 s[4:5], s[90:91], exec
	s_cselect_b32 s4, s3, s6
	s_lshl_b32 s4, s4, 3
	s_add_i32 s4, s34, s4
	v_mov_b32_e32 v0, s4
	ds_read_b32 v0, v0 offset:46080
	ds_read_b128 v[204:207], v203
	ds_read_b128 v[208:211], v203 offset:64
	ds_read_b128 v[212:215], v203 offset:2304
	ds_read_b128 v[216:219], v203 offset:2368
	ds_read_b128 v[224:227], v203 offset:4608
	ds_read_b128 v[242:245], v203 offset:4672
	s_waitcnt lgkmcnt(5)
	v_mfma_f32_16x16x32_bf16 v[204:207], v[56:59], v[204:207], 0
	v_lshlrev_b32_e32 v112, 16, v84
	v_and_b32_e32 v113, 0xffff0000, v84
	v_lshlrev_b32_e32 v84, 16, v85
	s_waitcnt lgkmcnt(4)
	v_mfma_f32_16x16x32_bf16 v[204:207], v[48:51], v[208:211], v[204:207]
	v_and_b32_e32 v85, 0xffff0000, v85
	v_lshlrev_b32_e32 v114, 16, v88
	v_and_b32_e32 v115, 0xffff0000, v88
	v_lshlrev_b32_e32 v88, 16, v89
	v_and_b32_e32 v89, 0xffff0000, v89
	v_fma_f32 v180, v180, v0, v84
	v_fma_f32 v181, v181, v0, v85
	s_nop 1
	v_fma_f32 v84, v72, v204, v114
	v_fma_f32 v85, v73, v205, v115
	v_fma_f32 v88, v74, v206, v88
	v_fma_f32 v89, v75, v207, v89
	s_waitcnt lgkmcnt(3)
	v_mfma_f32_16x16x32_bf16 v[204:207], v[56:59], v[212:215], 0
	v_fma_f32 v182, v182, v0, v112
	v_fma_f32 v183, v183, v0, v113
	v_lshlrev_b32_e32 v112, 16, v86
	v_and_b32_e32 v113, 0xffff0000, v86
	s_waitcnt lgkmcnt(2)
	v_mfma_f32_16x16x32_bf16 v[204:207], v[48:51], v[216:219], v[204:207]
	ds_read_b128 v[212:215], v203 offset:6912
	ds_read_b128 v[216:219], v203 offset:6976
	v_lshlrev_b32_e32 v86, 16, v87
	v_and_b32_e32 v87, 0xffff0000, v87
	v_lshlrev_b32_e32 v114, 16, v90
	v_and_b32_e32 v115, 0xffff0000, v90
	v_lshlrev_b32_e32 v90, 16, v91
	v_and_b32_e32 v91, 0xffff0000, v91
	v_fma_f32 v150, v150, v0, v86
	v_fma_f32 v151, v151, v0, v87
	s_nop 0
	v_fma_f32 v86, v72, v204, v114
	v_fma_f32 v87, v73, v205, v115
	v_fma_f32 v90, v74, v206, v90
	v_fma_f32 v91, v75, v207, v91
	s_waitcnt lgkmcnt(3)
	v_mfma_f32_16x16x32_bf16 v[204:207], v[56:59], v[224:227], 0
	v_fma_f32 v154, v154, v0, v112
	v_fma_f32 v155, v155, v0, v113
	v_lshlrev_b32_e32 v112, 16, v76
	v_and_b32_e32 v113, 0xffff0000, v76
	s_waitcnt lgkmcnt(2)
	v_mfma_f32_16x16x32_bf16 v[204:207], v[48:51], v[242:245], v[204:207]
	ds_read_b128 v[224:227], v203 offset:9216
	ds_read_b128 v[242:245], v203 offset:9280
	v_lshlrev_b32_e32 v76, 16, v77
	v_and_b32_e32 v77, 0xffff0000, v77
	v_lshlrev_b32_e32 v114, 16, v80
	v_and_b32_e32 v115, 0xffff0000, v80
	v_lshlrev_b32_e32 v80, 16, v81
	v_and_b32_e32 v81, 0xffff0000, v81
	v_fma_f32 v148, v148, v0, v76
	v_fma_f32 v149, v149, v0, v77
	s_nop 0
	v_fma_f32 v76, v72, v204, v114
	v_fma_f32 v77, v73, v205, v115
	v_fma_f32 v80, v74, v206, v80
	v_fma_f32 v81, v75, v207, v81
	s_waitcnt lgkmcnt(3)
	v_mfma_f32_16x16x32_bf16 v[204:207], v[56:59], v[212:215], 0
	v_fma_f32 v152, v152, v0, v112
	v_fma_f32 v153, v153, v0, v113
	v_lshlrev_b32_e32 v112, 16, v78
	v_and_b32_e32 v113, 0xffff0000, v78
	s_waitcnt lgkmcnt(2)
	v_mfma_f32_16x16x32_bf16 v[204:207], v[48:51], v[216:219], v[204:207]
	v_lshlrev_b32_e32 v78, 16, v79
	v_and_b32_e32 v79, 0xffff0000, v79
	v_lshlrev_b32_e32 v114, 16, v82
	v_and_b32_e32 v115, 0xffff0000, v82
	v_lshlrev_b32_e32 v82, 16, v83
	v_and_b32_e32 v83, 0xffff0000, v83
	v_fma_f32 v184, v184, v0, v78
	v_fma_f32 v185, v185, v0, v79
	s_nop 0
	v_fma_f32 v78, v72, v204, v114
	v_fma_f32 v79, v73, v205, v115
	v_fma_f32 v82, v74, v206, v82
	v_fma_f32 v83, v75, v207, v83
	s_waitcnt lgkmcnt(1)
	v_mfma_f32_16x16x32_bf16 v[204:207], v[56:59], v[224:227], 0
	v_lshlrev_b32_e32 v116, 16, v2
	v_and_b32_e32 v117, 0xffff0000, v2
	v_lshlrev_b32_e32 v2, 16, v3
	s_waitcnt lgkmcnt(0)
	v_mfma_f32_16x16x32_bf16 v[204:207], v[48:51], v[242:245], v[204:207]
	v_and_b32_e32 v3, 0xffff0000, v3
	v_fma_f32 v160, v160, v0, v112
	v_fma_f32 v161, v161, v0, v113
	v_lshlrev_b32_e32 v112, 16, v144
	v_and_b32_e32 v113, 0xffff0000, v144
	v_lshlrev_b32_e32 v114, 16, v145
	s_nop 2
	v_fma_f32 v204, v72, v204, v116
	v_fma_f32 v205, v73, v205, v117
	v_fma_f32 v2, v74, v206, v2
	v_fma_f32 v3, v75, v207, v3
	v_and_b32_e32 v115, 0xffff0000, v145
	v_mov_b32_dpp v206, v204 row_newbcast:1 row_mask:0xf bank_mask:0xf bound_ctrl:1
	v_max_f32_dpp v204, |v204|, v206 row_newbcast:0 row_mask:0xf bank_mask:0xf bound_ctrl:1
	v_rcp_f32_e32 v204, v204
	v_mov_b32_dpp v206, v205 row_newbcast:1 row_mask:0xf bank_mask:0xf bound_ctrl:1
	v_max_f32_dpp v205, |v205|, v206 row_newbcast:0 row_mask:0xf bank_mask:0xf bound_ctrl:1
	v_rcp_f32_e32 v205, v205
	v_mov_b32_dpp v206, v2 row_newbcast:1 row_mask:0xf bank_mask:0xf bound_ctrl:1
	v_max_f32_dpp v2, |v2|, v206 row_newbcast:0 row_mask:0xf bank_mask:0xf bound_ctrl:1
	v_rcp_f32_e32 v206, v2
	v_fma_f32 v156, v156, v0, v114
	v_fma_f32 v157, v157, v0, v115
	v_mov_b32_dpp v2, v3 row_newbcast:1 row_mask:0xf bank_mask:0xf bound_ctrl:1
	v_max_f32_dpp v2, |v3|, v2 row_newbcast:0 row_mask:0xf bank_mask:0xf bound_ctrl:1
	v_rcp_f32_e32 v207, v2
	v_fma_f32 v158, v158, v0, v112
	v_fma_f32 v159, v159, v0, v113
	v_pk_mul_f32 v[50:51], v[84:85], v[204:205]
	v_pk_mul_f32 v[112:113], v[86:87], v[204:205]
	v_pk_mul_f32 v[2:3], v[88:89], v[206:207]
	v_pk_mul_f32 v[118:119], v[90:91], v[206:207]
	v_pk_mul_f32 v[48:49], v[80:81], v[206:207]
	v_pk_mul_f32 v[56:57], v[76:77], v[204:205]
	v_pk_mul_f32 v[116:117], v[82:83], v[206:207]
	v_pk_mul_f32 v[114:115], v[78:79], v[204:205]
	s_branch .LBB0_413

; template <bool GDN, int NT> __device__ __forceinline__ void scan_load(const Frame& F, int b, int h, int dir, const ScanLane& L, int s, ScanOps<NT>& o) {
;     ...
;         const char* zq = upin((const char*)F.Z + ((size_t)chunk_row0(b, cidx) * ZW + ZC_LQ + h * 64) * 2);
; #pragma unroll
;         for (int ks = 0; ks < 2; ++ks) { o.Qf[ks] = ldu<bf16x8>(zq + ks * 64, L.zq); o.Mf[ks] = o.Qf[ks]; }
;         const char* base = (const char*)F.PM + (size_t)ud * 20480;
;         const char* bO = upin(base); const char* bB = upin(base + 10240);
; #pragma unroll
;         for (int pr = 0; pr < 2; ++pr) { const v4u qb = ldun<v4u>(bB + pr * 1024, L.o16p), qo = ldun<v4u>(bO + pr * 1024, L.o16p);
;             o.bv[2 * pr] = (v2u){qb.x, qb.y}; o.bv[2 * pr + 1] = (v2u){qb.z, qb.w}; o.ov[2 * pr] = (v2u){qo.x, qo.y}; o.ov[2 * pr + 1] = (v2u){qo.z, qo.w}; }
;         o.bv[4] = ldun<v2u>(bB + 2048, L.o8); o.ov[4] = ldun<v2u>(bO + 2048, L.o8);
;         o.wi = ldu<f32x4>(upin((const char*)F.WI + (size_t)ud * 256), L.wi);
;     ...
;     LAS bf16_t* Sb = St + ((dir * 2 + (s & 1)) * 80) * 72;
;     if (s < 36) {
; #pragma unroll
;         for (int t = 0; t < NT; ++t) *(LAS v2u*)(Sb + (16 * t + lr) * 72 + 16 * wq + 4 * lq) = pack4(S[t]); }
;     if (s == 21 || s == 3) asm volatile("s_waitcnt vmcnt(0)" ::: "memory");
;     else if (scan_needfin(s - 1)) { if (GDN) asm volatile("s_waitcnt vmcnt(14)" ::: "memory"); else asm volatile("s_waitcnt vmcnt(15)" ::: "memory"); }
;     else { if (GDN) asm volatile("s_waitcnt vmcnt(8)" ::: "memory"); else asm volatile("s_waitcnt vmcnt(9)" ::: "memory"); }
;     __syncthreads();
;     if (s > 0) {
;         const int sp = s - 1;
;         if (sp == 20 || sp == 2) { asm volatile("s_waitcnt vmcnt(0)" ::: "memory"); scan_fin_load<GDN>(F, b, h, dir, L, sp, PEND, fin); }
;         if (!nofin) scan_finish<GDN>(F, b, h, dir, L, sp, PEND, Oprev, fin);
;     }
;     if (s == 36) return false;
;     if (scan_needfin(s) && ko != 1 && ko != 3) scan_fin_load<GDN>(F, b, h, dir, L, s + 1, PEND, fin);
;     if (ko != 1 && ko != 2) scan_load<GDN, NT>(F, b, h, dir, L, s < 34 ? s + 2 : 35, ld);
;     const float gl = ((const LAS float*)(St + 4 * 80 * 72))[(dir ? (s < 4 ? 3 - s : 39 - s) : s) * 2 + dir];
;     f32x4 O[NT];
; #pragma unroll
;     for (int t = 0; t < NT; ++t) {
;         const LAS bf16_t* sp2 = Sb + (16 * t + lr) * 72 + 8 * lq;
.LBB0_437:
	s_add_i32 s8, s25, 3
	s_min_u32 s4, s8, 33
	s_add_i32 s6, s4, 2
	s_sub_i32 s7, 37, s4
	s_and_b64 s[4:5], s[90:91], exec
	s_cselect_b32 s4, s6, s7
	s_lshl_b32 s5, s4, 6
	s_add_i32 s5, s5, s33
	s_add_i32 s4, s4, s31
	s_lshl_b32 s4, s4, 1
	s_mulk_i32 s5, 0xd00
	s_add_i32 s92, s4, s68
	s_or_b32 s4, s36, s5
	s_mov_b32 s5, s37
	s_lshl_b64 s[4:5], s[4:5], 1
	s_add_u32 s4, s16, s4
	s_addc_u32 s5, s17, s5
	global_load_dwordx4 v[56:59], v74, s[4:5]
	global_load_dwordx4 v[48:51], v74, s[4:5] offset:64
	s_mul_i32 s4, s92, 0x5000
	v_readlane_b32 s6, v254, 46
	s_mul_hi_u32 s5, s92, 0x5000
	s_add_u32 s4, s6, s4
	v_readlane_b32 s6, v254, 47
	s_addc_u32 s5, s6, s5
	s_mov_b64 s[6:7], s[4:5]
	s_add_u32 s4, s4, 0x2800
	s_addc_u32 s5, s5, 0
	global_load_dwordx4 v[84:87], v73, s[4:5] nt
	global_load_dwordx4 v[76:79], v73, s[4:5] offset:1024 nt
	global_load_dwordx4 v[88:91], v73, s[6:7] nt
	global_load_dwordx4 v[80:83], v73, s[6:7] offset:1024 nt
	global_load_dwordx2 v[144:145], v72, s[4:5] offset:2048 nt
	global_load_dwordx2 v[2:3], v72, s[6:7] offset:2048 nt
	s_lshl_b64 s[4:5], s[92:93], 8
	v_readlane_b32 s6, v254, 52
	v_readlane_b32 s7, v254, 53
	s_add_u32 s4, s6, s4
	s_addc_u32 s5, s7, s5
	global_load_dwordx4 v[72:75], v0, s[4:5]
	s_add_i32 s1, s1, s24
	s_and_b64 s[4:5], s[90:91], exec
	s_cselect_b32 s1, s8, s1
	ds_read_b128 v[104:107], v203 offset:11520
	s_lshl_b32 s4, s1, 3
	s_add_i32 s4, s34, s4
	v_mov_b32_e32 v0, s4
	ds_read_b32 v0, v0 offset:46080
	ds_read_b128 v[108:111], v203 offset:11584
	ds_read_b128 v[212:215], v203 offset:13824
	ds_read_b128 v[216:219], v203 offset:13888
	ds_read_b128 v[224:227], v203 offset:16128
	ds_read_b128 v[242:245], v203 offset:16192
	s_waitcnt lgkmcnt(6)
	v_mfma_f32_16x16x32_bf16 v[104:107], v[40:43], v[104:107], 0
	v_lshlrev_b32_e32 v112, 16, v92
	v_and_b32_e32 v113, 0xffff0000, v92
	v_lshlrev_b32_e32 v114, 16, v93
	s_waitcnt lgkmcnt(4)
	v_mfma_f32_16x16x32_bf16 v[104:107], v[36:39], v[108:111], v[104:107]
	v_and_b32_e32 v115, 0xffff0000, v93
	v_fma_f32 v192, v180, v0, v114
	v_fma_f32 v193, v181, v0, v115
	v_fma_f32 v190, v182, v0, v112
	v_fma_f32 v191, v183, v0, v113
	s_waitcnt lgkmcnt(3)
	v_mfma_f32_16x16x32_bf16 v[108:111], v[40:43], v[212:215], 0
	v_lshlrev_b32_e32 v116, 16, v94
	v_and_b32_e32 v117, 0xffff0000, v94
	v_lshlrev_b32_e32 v118, 16, v95
	s_waitcnt lgkmcnt(2)
	v_mfma_f32_16x16x32_bf16 v[108:111], v[36:39], v[216:219], v[108:111]
	ds_read_b128 v[212:215], v203 offset:18432
	ds_read_b128 v[216:219], v203 offset:18496
	v_and_b32_e32 v119, 0xffff0000, v95
	v_fma_f32 v188, v150, v0, v118
	v_fma_f32 v189, v151, v0, v119
	v_fma_f32 v154, v154, v0, v116
	v_fma_f32 v155, v155, v0, v117
	s_waitcnt lgkmcnt(3)
	v_mfma_f32_16x16x32_bf16 v[112:115], v[40:43], v[224:227], 0
	v_lshlrev_b32_e32 v150, 16, v64
	v_and_b32_e32 v151, 0xffff0000, v64
	v_lshlrev_b32_e32 v162, 16, v65
	s_waitcnt lgkmcnt(2)
	v_mfma_f32_16x16x32_bf16 v[112:115], v[36:39], v[242:245], v[112:115]
	ds_read_b128 v[224:227], v203 offset:20736
	ds_read_b128 v[242:245], v203 offset:20800
	v_and_b32_e32 v163, 0xffff0000, v65
	v_fma_f32 v186, v148, v0, v162
	v_fma_f32 v187, v149, v0, v163
	v_fma_f32 v182, v152, v0, v150
	v_fma_f32 v183, v153, v0, v151
	s_waitcnt lgkmcnt(3)
	v_mfma_f32_16x16x32_bf16 v[116:119], v[40:43], v[212:215], 0
	v_lshlrev_b32_e32 v152, 16, v66
	v_and_b32_e32 v153, 0xffff0000, v66
	v_lshlrev_b32_e32 v168, 16, v142
	s_waitcnt lgkmcnt(2)
	v_mfma_f32_16x16x32_bf16 v[116:119], v[36:39], v[216:219], v[116:119]
	v_and_b32_e32 v169, 0xffff0000, v142
	v_lshlrev_b32_e32 v170, 16, v143
	s_waitcnt lgkmcnt(1)
	v_mfma_f32_16x16x32_bf16 v[148:151], v[40:43], v[224:227], 0
	v_and_b32_e32 v171, 0xffff0000, v143
	v_lshlrev_b32_e32 v162, 16, v67
	v_and_b32_e32 v163, 0xffff0000, v67
	s_waitcnt lgkmcnt(0)
	v_mfma_f32_16x16x32_bf16 v[148:151], v[36:39], v[242:245], v[148:151]
	v_fma_f32 v178, v160, v0, v152
	v_fma_f32 v179, v161, v0, v153
	v_lshlrev_b32_e32 v152, 16, v146
	v_and_b32_e32 v153, 0xffff0000, v146
	v_lshlrev_b32_e32 v160, 16, v147
	v_and_b32_e32 v161, 0xffff0000, v147
	s_nop 0
	v_fma_f32 v150, v62, v150, v170
	v_fma_f32 v151, v63, v151, v171
	v_fma_f32 v148, v60, v148, v168
	v_fma_f32 v149, v61, v149, v169
	v_fma_f32 v162, v184, v0, v162
	v_fma_f32 v163, v185, v0, v163
	v_fma_f32 v164, v156, v0, v160
	v_fma_f32 v165, v157, v0, v161
	v_fma_f32 v180, v158, v0, v152
	v_fma_f32 v181, v159, v0, v153
	v_mov_b32_dpp v184, v148 row_newbcast:0 row_mask:0xf bank_mask:0xf bound_ctrl:1
	v_mov_b32_dpp v185, v148 row_newbcast:1 row_mask:0xf bank_mask:0xf bound_ctrl:1
	v_mov_b32_dpp v160, v149 row_newbcast:0 row_mask:0xf bank_mask:0xf bound_ctrl:1
	v_mov_b32_dpp v161, v149 row_newbcast:1 row_mask:0xf bank_mask:0xf bound_ctrl:1
	v_mov_b32_dpp v158, v150 row_newbcast:0 row_mask:0xf bank_mask:0xf bound_ctrl:1
	v_mov_b32_dpp v159, v150 row_newbcast:1 row_mask:0xf bank_mask:0xf bound_ctrl:1
	v_mov_b32_dpp v156, v151 row_newbcast:0 row_mask:0xf bank_mask:0xf bound_ctrl:1
	v_mov_b32_dpp v157, v151 row_newbcast:1 row_mask:0xf bank_mask:0xf bound_ctrl:1
	v_mov_b32_e32 v148, v194
	v_mov_b32_e32 v150, v196
	v_mov_b32_e32 v152, v199
	v_mov_b32_e32 v166, v198
	v_mov_b32_e32 v153, v200
	v_mov_b32_e32 v149, v195
	v_mov_b32_e32 v0, v120
	v_mov_b32_e32 v151, v197
	s_cmp_gt_u32 s25, 31
	s_cbranch_scc1 .LBB0_451
	v_cvt_pk_bf16_f32 v166, v190, v191
	v_cvt_pk_bf16_f32 v167, v192, v193
	ds_write_b64 v202, v[166:167]
	v_cvt_pk_bf16_f32 v166, v154, v155
	v_cvt_pk_bf16_f32 v167, v188, v189
	ds_write_b64 v202, v[166:167] offset:2304
	v_cvt_pk_bf16_f32 v166, v182, v183
	v_cvt_pk_bf16_f32 v167, v186, v187
	ds_write_b64 v202, v[166:167] offset:4608
	v_cvt_pk_bf16_f32 v166, v178, v179
	v_cvt_pk_bf16_f32 v167, v162, v163
	ds_write_b64 v202, v[166:167] offset:6912
	v_cvt_pk_bf16_f32 v166, v180, v181
	v_cvt_pk_bf16_f32 v167, v164, v165
	ds_write_b64 v202, v[166:167] offset:9216
	s_sub_i32 s4, s25, 17
	s_cmp_gt_u32 s4, 14
	s_mov_b64 s[10:11], -1
	s_cbranch_scc1 .LBB0_452

; template <bool GDN, int NT> __device__ __forceinline__ void scan_load(const Frame& F, int b, int h, int dir, const ScanLane& L, int s, ScanOps<NT>& o) {
;     ...
;         const char* zq = upin((const char*)F.Z + ((size_t)chunk_row0(b, cidx) * ZW + ZC_LQ + h * 64) * 2);
; #pragma unroll
;         for (int ks = 0; ks < 2; ++ks) { o.Qf[ks] = ldu<bf16x8>(zq + ks * 64, L.zq); o.Mf[ks] = o.Qf[ks]; }
;         const char* base = (const char*)F.PM + (size_t)ud * 20480;
;         const char* bO = upin(base); const char* bB = upin(base + 10240);
; #pragma unroll
;         for (int pr = 0; pr < 2; ++pr) { const v4u qb = ldun<v4u>(bB + pr * 1024, L.o16p), qo = ldun<v4u>(bO + pr * 1024, L.o16p);
;             o.bv[2 * pr] = (v2u){qb.x, qb.y}; o.bv[2 * pr + 1] = (v2u){qb.z, qb.w}; o.ov[2 * pr] = (v2u){qo.x, qo.y}; o.ov[2 * pr + 1] = (v2u){qo.z, qo.w}; }
;         o.bv[4] = ldun<v2u>(bB + 2048, L.o8); o.ov[4] = ldun<v2u>(bO + 2048, L.o8);
;         o.wi = ldu<f32x4>(upin((const char*)F.WI + (size_t)ud * 256), L.wi);
;     ...
;     const float gl = ((const LAS float*)(St + 4 * 80 * 72))[(dir ? (s < 4 ? 3 - s : 39 - s) : s) * 2 + dir];
;     f32x4 O[NT];
; #pragma unroll
;     for (int t = 0; t < NT; ++t) {
;         const LAS bf16_t* sp2 = Sb + (16 * t + lr) * 72 + 8 * lq;
;         const bf16x8 s0 = *(const LAS bf16x8*)sp2, s1 = *(const LAS bf16x8*)(sp2 + 32);
;         const f32x4 bv = unpack4(use.bv[t]), ov = unpack4(use.ov[t]);
;         if (GDN) {
;             f32x4 o = ov, sn = S[t] * gl + bv;
;             o = __builtin_amdgcn_mfma_f32_16x16x32_bf16(use.Qf[0], s0, o, 0, 0, 0); o = __builtin_amdgcn_mfma_f32_16x16x32_bf16(use.Qf[1], s1, o, 0, 0, 0);
;             sn = __builtin_amdgcn_mfma_f32_16x16x32_bf16(use.Mf[0], s0, sn, 0, 0, 0); sn = __builtin_amdgcn_mfma_f32_16x16x32_bf16(use.Mf[1], s1, sn, 0, 0, 0);
;             S[t] = sn; O[t] = o;
;         } else {
;             f32x4 o = {0.f, 0.f, 0.f, 0.f};
;             o = __builtin_amdgcn_mfma_f32_16x16x32_bf16(use.Qf[0], s0, o, 0, 0, 0); o = __builtin_amdgcn_mfma_f32_16x16x32_bf16(use.Qf[1], s1, o, 0, 0, 0);
;             S[t] = S[t] * gl + bv; O[t] = o * use.wi + ov; }
;     }
;     if (!GDN) {
; #pragma unroll
;         for (int i = 0; i < 4; ++i) { const float den = row16_bcast<0>(O[NT - 1][i]), fl = row16_bcast<1>(O[NT - 1][i]); const float dv = frcp(fmaxf(fabsf(den), fl));
; #pragma unroll
.LBB0_446:
	s_min_u32 s0, s3, 33
	s_add_i32 s4, s0, 2
	s_sub_i32 s5, 37, s0
	s_and_b64 s[0:1], s[90:91], exec
	s_cselect_b32 s0, s4, s5
	s_lshl_b32 s1, s0, 6
	s_add_i32 s1, s1, s33
	s_add_i32 s0, s0, s31
	s_lshl_b32 s0, s0, 1
	s_mulk_i32 s1, 0xd00
	s_add_i32 s92, s0, s68
	s_or_b32 s0, s36, s1
	s_mov_b32 s1, s37
	s_lshl_b64 s[0:1], s[0:1], 1
	s_add_u32 s0, s16, s0
	s_addc_u32 s1, s17, s1
	global_load_dwordx4 v[40:43], v150, s[0:1]
	global_load_dwordx4 v[36:39], v150, s[0:1] offset:64
	s_mul_i32 s0, s92, 0x5000
	v_readlane_b32 s4, v254, 46
	s_mul_hi_u32 s1, s92, 0x5000
	s_add_u32 s0, s4, s0
	v_readlane_b32 s4, v254, 47
	s_addc_u32 s1, s4, s1
	s_mov_b64 s[4:5], s[0:1]
	s_add_u32 s0, s0, 0x2800
	s_addc_u32 s1, s1, 0
	global_load_dwordx4 v[92:95], v149, s[0:1] nt
	global_load_dwordx4 v[64:67], v149, s[0:1] offset:1024 nt
	global_load_dwordx4 v[96:99], v149, s[4:5] nt
	global_load_dwordx4 v[68:71], v149, s[4:5] offset:1024 nt
	global_load_dwordx2 v[146:147], v148, s[0:1] offset:2048 nt
	global_load_dwordx2 v[142:143], v148, s[4:5] offset:2048 nt
	s_lshl_b64 s[0:1], s[92:93], 8
	v_readlane_b32 s4, v254, 52
	v_readlane_b32 s5, v254, 53
	s_add_u32 s0, s4, s0
	s_addc_u32 s1, s5, s1
	s_add_i32 s4, s24, 38
	global_load_dwordx4 v[60:63], v0, s[0:1]
	s_and_b64 s[0:1], s[90:91], exec
	s_cselect_b32 s0, s3, s4
	s_lshl_b32 s0, s0, 3
	s_add_i32 s0, s34, s0
	v_mov_b32_e32 v0, s0
	ds_read_b32 v0, v0 offset:46080
	ds_read_b128 v[104:107], v203
	ds_read_b128 v[108:111], v203 offset:64
	ds_read_b128 v[212:215], v203 offset:2304
	ds_read_b128 v[216:219], v203 offset:2368
	ds_read_b128 v[224:227], v203 offset:4608
	ds_read_b128 v[242:245], v203 offset:4672
	s_waitcnt lgkmcnt(5)
	v_mfma_f32_16x16x32_bf16 v[104:107], v[24:27], v[104:107], 0
	v_lshlrev_b32_e32 v112, 16, v44
	v_and_b32_e32 v113, 0xffff0000, v44
	v_lshlrev_b32_e32 v114, 16, v52
	s_waitcnt lgkmcnt(4)
	v_mfma_f32_16x16x32_bf16 v[104:107], v[20:23], v[108:111], v[104:107]
	v_and_b32_e32 v115, 0xffff0000, v52
	v_lshlrev_b32_e32 v52, 16, v53
	v_and_b32_e32 v53, 0xffff0000, v53
	v_fma_f32 v190, v190, v0, v112
	v_fma_f32 v191, v191, v0, v113
	v_lshlrev_b32_e32 v44, 16, v45
	s_nop 2
	v_fma_f32 v112, v100, v104, v114
	v_fma_f32 v113, v101, v105, v115
	v_fma_f32 v114, v102, v106, v52
	v_fma_f32 v115, v103, v107, v53
	v_and_b32_e32 v45, 0xffff0000, v45
	v_fma_f32 v192, v192, v0, v44
	v_fma_f32 v193, v193, v0, v45
	v_lshlrev_b32_e32 v52, 16, v46
	v_and_b32_e32 v53, 0xffff0000, v46
	v_lshlrev_b32_e32 v116, 16, v47
	v_and_b32_e32 v117, 0xffff0000, v47
	s_waitcnt lgkmcnt(3)
	v_mfma_f32_16x16x32_bf16 v[44:47], v[24:27], v[212:215], 0
	v_lshlrev_b32_e32 v118, 16, v54
	v_and_b32_e32 v119, 0xffff0000, v54
	v_lshlrev_b32_e32 v54, 16, v55
	s_waitcnt lgkmcnt(2)
	v_mfma_f32_16x16x32_bf16 v[44:47], v[20:23], v[216:219], v[44:47]
	ds_read_b128 v[212:215], v203 offset:6912
	ds_read_b128 v[216:219], v203 offset:6976
	v_and_b32_e32 v55, 0xffff0000, v55
	v_fma_f32 v154, v154, v0, v52
	v_fma_f32 v155, v155, v0, v53
	v_lshlrev_b32_e32 v108, 16, v28
	v_and_b32_e32 v109, 0xffff0000, v28
	v_lshlrev_b32_e32 v110, 16, v32
	s_nop 2
	v_fma_f32 v104, v100, v44, v118
	v_fma_f32 v105, v101, v45, v119
	v_fma_f32 v106, v102, v46, v54
	v_fma_f32 v107, v103, v47, v55
	s_waitcnt lgkmcnt(3)
	v_mfma_f32_16x16x32_bf16 v[44:47], v[24:27], v[224:227], 0
	v_and_b32_e32 v111, 0xffff0000, v32
	v_lshlrev_b32_e32 v32, 16, v33
	v_and_b32_e32 v33, 0xffff0000, v33
	s_waitcnt lgkmcnt(2)
	v_mfma_f32_16x16x32_bf16 v[44:47], v[20:23], v[242:245], v[44:47]
	ds_read_b128 v[224:227], v203 offset:9216
	ds_read_b128 v[242:245], v203 offset:9280
	v_fma_f32 v188, v188, v0, v116
	v_fma_f32 v189, v189, v0, v117
	v_fma_f32 v182, v182, v0, v108
	v_fma_f32 v183, v183, v0, v109
	v_lshlrev_b32_e32 v28, 16, v29
	v_and_b32_e32 v29, 0xffff0000, v29
	v_fma_f32 v186, v186, v0, v28
	v_fma_f32 v187, v187, v0, v29
	s_nop 1
	v_fma_f32 v108, v100, v44, v110
	v_fma_f32 v109, v101, v45, v111
	v_fma_f32 v116, v102, v46, v32
	v_fma_f32 v117, v103, v47, v33
	v_lshlrev_b32_e32 v32, 16, v30
	v_and_b32_e32 v33, 0xffff0000, v30
	v_lshlrev_b32_e32 v110, 16, v31
	v_and_b32_e32 v111, 0xffff0000, v31
	s_waitcnt lgkmcnt(3)
	v_mfma_f32_16x16x32_bf16 v[28:31], v[24:27], v[212:215], 0
	v_lshlrev_b32_e32 v118, 16, v34
	v_and_b32_e32 v119, 0xffff0000, v34
	v_lshlrev_b32_e32 v34, 16, v35
	s_waitcnt lgkmcnt(2)
	v_mfma_f32_16x16x32_bf16 v[28:31], v[20:23], v[216:219], v[28:31]
	v_and_b32_e32 v35, 0xffff0000, v35
	v_fma_f32 v178, v178, v0, v32
	v_fma_f32 v179, v179, v0, v33
	v_fma_f32 v162, v162, v0, v110
	v_fma_f32 v163, v163, v0, v111
	v_lshlrev_b32_e32 v110, 16, v138
	v_and_b32_e32 v111, 0xffff0000, v138
	s_nop 2
	v_fma_f32 v44, v100, v28, v118
	v_fma_f32 v45, v101, v29, v119
	v_fma_f32 v46, v102, v30, v34
	v_fma_f32 v47, v103, v31, v35
	s_waitcnt lgkmcnt(1)
	v_mfma_f32_16x16x32_bf16 v[24:27], v[24:27], v[224:227], 0
	v_lshlrev_b32_e32 v28, 16, v139
	v_and_b32_e32 v29, 0xffff0000, v139
	v_lshlrev_b32_e32 v52, 16, v140
	s_waitcnt lgkmcnt(0)
	v_mfma_f32_16x16x32_bf16 v[20:23], v[20:23], v[242:245], v[24:27]
	v_and_b32_e32 v53, 0xffff0000, v140
	v_lshlrev_b32_e32 v54, 16, v141
	v_and_b32_e32 v55, 0xffff0000, v141
	v_fma_f32 v164, v164, v0, v54
	v_fma_f32 v165, v165, v0, v55
	v_fma_f32 v180, v180, v0, v52
	v_fma_f32 v181, v181, v0, v53
	s_nop 2
	v_fma_f32 v20, v100, v20, v110
	v_fma_f32 v21, v101, v21, v111
	v_fma_f32 v22, v102, v22, v28
	v_fma_f32 v23, v103, v23, v29
	s_nop 0
	v_mov_b32_dpp v24, v20 row_newbcast:1 row_mask:0xf bank_mask:0xf bound_ctrl:1
	v_max_f32_dpp v20, |v20|, v24 row_newbcast:0 row_mask:0xf bank_mask:0xf bound_ctrl:1
	v_rcp_f32_e32 v28, v20
	s_nop 0
	v_mov_b32_dpp v20, v21 row_newbcast:1 row_mask:0xf bank_mask:0xf bound_ctrl:1
	v_max_f32_dpp v20, |v21|, v20 row_newbcast:0 row_mask:0xf bank_mask:0xf bound_ctrl:1
	v_mov_b32_dpp v21, v22 row_newbcast:1 row_mask:0xf bank_mask:0xf bound_ctrl:1
	v_max_f32_dpp v21, |v22|, v21 row_newbcast:0 row_mask:0xf bank_mask:0xf bound_ctrl:1
	v_rcp_f32_e32 v30, v21
	v_mov_b32_dpp v22, v23 row_newbcast:1 row_mask:0xf bank_mask:0xf bound_ctrl:1
	v_mov_b32_dpp v21, v23 row_newbcast:0 row_mask:0xf bank_mask:0xf bound_ctrl:1
	v_max_f32_e64 v21, |v21|, v22
	v_rcp_f32_e32 v31, v21
	v_rcp_f32_e32 v29, v20
	v_pk_mul_f32 v[20:21], v[114:115], v[30:31]
	v_pk_mul_f32 v[24:25], v[112:113], v[28:29]
	v_pk_mul_f32 v[110:111], v[106:107], v[30:31]
	v_pk_mul_f32 v[104:105], v[104:105], v[28:29]
	v_pk_mul_f32 v[22:23], v[116:117], v[30:31]
	v_pk_mul_f32 v[26:27], v[108:109], v[28:29]
	v_pk_mul_f32 v[108:109], v[46:47], v[30:31]
	v_pk_mul_f32 v[106:107], v[44:45], v[28:29]
	s_branch .LBB0_456
